# v046 + static s_setprio 1 for waves 4-7 during the attention tile loop
# speedup vs baseline: 1.0015x; 1.0015x over previous
.LBB0_558:
	v_ashrrev_i32_e32 v179, 4, v166
	s_waitcnt vmcnt(7)
	v_and_b32_e32 v4, 0xfffff0, v179
	v_lshlrev_b32_e32 v5, 1, v179
	v_lshlrev_b32_e32 v2, 3, v166
	v_and_or_b32 v4, v5, 8, v4
	v_and_b32_e32 v3, 0x78, v2
	v_lshrrev_b32_e32 v5, 1, v179
	v_lshrrev_b32_e32 v4, 1, v4
	v_bfe_u32 v2, v2, 5, 2
	s_waitcnt vmcnt(6)
	v_and_b32_e32 v6, 3, v179
	v_or_b32_e32 v4, v4, v2
	v_and_or_b32 v5, v5, 4, v6
	v_lshlrev_b32_e32 v130, 1, v3
	v_lshlrev_b32_e32 v4, 9, v4
	v_lshlrev_b32_e32 v5, 6, v5
	v_and_b32_e32 v3, 48, v130
	v_add_u32_e32 v181, 32, v179
	s_waitcnt vmcnt(3)
	v_or3_b32 v18, v4, v5, v3
	v_and_b32_e32 v4, 0xfffff0, v181
	v_lshlrev_b32_e32 v6, 1, v181
	v_and_or_b32 v4, v6, 8, v4
	v_lshrrev_b32_e32 v4, 1, v4
	v_or_b32_e32 v2, v4, v2
	v_and_b32_e32 v165, 63, v166
	v_lshlrev_b32_e32 v2, 9, v2
	v_or3_b32 v19, v2, v5, v3
	v_lshlrev_b32_e32 v3, 4, v165
	s_and_b32 s0, s40, 0x3fffffc0
	v_lshlrev_b32_e32 v2, 3, v165
	v_and_b32_e32 v3, 0xc0, v3
	v_lshlrev_b32_e32 v4, 1, v165
	s_lshl_b32 s0, s0, 2
	v_and_or_b32 v3, v2, 24, v3
	v_and_b32_e32 v4, 32, v4
	v_and_b32_e32 v2, 0x100, v2
	s_add_i32 s70, s0, 0
	v_or3_b32 v171, v3, v4, v2
	v_mad_i64_i32 v[2:3], s[0:1], s28, v179, 0
	v_lshlrev_b64 v[34:35], 1, v[2:3]
	v_lshl_add_u64 v[2:3], s[50:51], 0, v[34:35]
	v_lshl_add_u64 v[2:3], v[2:3], 0, v[130:131]
	v_mad_i64_i32 v[6:7], s[0:1], s28, v181, 0
	v_lshlrev_b64 v[36:37], 1, v[6:7]
	v_lshl_add_u64 v[6:7], s[50:51], 0, v[36:37]
	v_lshl_add_u64 v[10:11], s[96:97], 0, v[34:35]
	v_lshl_add_u64 v[14:15], s[96:97], 0, v[36:37]
	v_lshl_add_u64 v[6:7], v[6:7], 0, v[130:131]
	v_lshl_add_u64 v[10:11], v[10:11], 0, v[130:131]
	v_lshl_add_u64 v[14:15], v[14:15], 0, v[130:131]
	v_add_u32_e32 v187, 0, v18
	v_add_u32_e32 v188, 0, v19
	s_waitcnt vmcnt(0)
	s_movk_i32 s0, 0xf0
	v_lshl_add_u32 v47, v167, 8, 0
	s_add_i32 s70, s70, 0x10000
	v_add_u32_e32 v176, 0, v171
	v_lshl_add_u32 v177, v167, 2, s70
	v_lshlrev_b32_e32 v2, 8, v179
	v_and_b32_e32 v3, 0xf0, v166
	v_bitop3_b32 v2, v130, v2, v3 bitop3:0xde
	v_add_u32_e32 v191, 0, v2
	v_lshlrev_b32_e32 v2, 8, v181
	v_bitop3_b32 v2, v130, v2, v3 bitop3:0xde
	v_add_u32_e32 v192, 0, v2
	v_lshlrev_b32_e32 v2, 4, v167
	v_and_b32_e32 v46, 0xf0, v2
	v_bitop3_b32 v2, v164, v2, s0 bitop3:0x78
	v_add_u32_e32 v180, v47, v2
	s_waitcnt lgkmcnt(0)
	s_barrier
	ds_read_b128 v[2:5], v180 offset:32768
	ds_read_b128 v[6:9], v180 offset:40960
	s_waitcnt lgkmcnt(1)
	v_mfma_f32_32x32x16_bf16 v[18:33], v[2:5], v[136:139], 0
	v_bitop3_b32 v38, v164, v46, 32 bitop3:0x36
	v_add_u32_e32 v182, v47, v38
	ds_read_b128 v[38:41], v182 offset:32768
	ds_read_b128 v[42:45], v182 offset:40960
	s_movk_i32 s0, 0x60
	s_waitcnt lgkmcnt(2)
	v_mfma_f32_32x32x16_bf16 v[2:17], v[6:9], v[136:139], 0
	s_waitcnt lgkmcnt(1)
	v_mfma_f32_32x32x16_bf16 v[18:33], v[38:41], v[144:147], v[18:33]
	v_bitop3_b32 v38, v164, v46, 64 bitop3:0x36
	v_add_u32_e32 v183, v47, v38
	s_waitcnt lgkmcnt(0)
	v_mfma_f32_32x32x16_bf16 v[2:17], v[42:45], v[144:147], v[2:17]
	ds_read_b128 v[38:41], v183 offset:32768
	ds_read_b128 v[42:45], v183 offset:40960
	s_waitcnt lgkmcnt(1)
	v_mfma_f32_32x32x16_bf16 v[18:33], v[38:41], v[132:135], v[18:33]
	v_bitop3_b32 v38, v164, v46, s0 bitop3:0x36
	v_add_u32_e32 v184, v47, v38
	s_movk_i32 s0, 0x80
	s_waitcnt lgkmcnt(0)
	v_mfma_f32_32x32x16_bf16 v[2:17], v[42:45], v[132:135], v[2:17]
	ds_read_b128 v[38:41], v184 offset:32768
	ds_read_b128 v[42:45], v184 offset:40960
	s_waitcnt lgkmcnt(1)
	v_mfma_f32_32x32x16_bf16 v[18:33], v[38:41], v[140:143], v[18:33]
	v_bitop3_b32 v38, v164, v46, s0 bitop3:0x36
	v_add_u32_e32 v185, v47, v38
	s_movk_i32 s0, 0xa0
	s_waitcnt lgkmcnt(0)
	v_mfma_f32_32x32x16_bf16 v[2:17], v[42:45], v[140:143], v[2:17]
	ds_read_b128 v[38:41], v185 offset:32768
	ds_read_b128 v[42:45], v185 offset:40960
	s_waitcnt lgkmcnt(1)
	v_mfma_f32_32x32x16_bf16 v[18:33], v[38:41], v[152:155], v[18:33]
	v_bitop3_b32 v38, v164, v46, s0 bitop3:0x36
	v_add_u32_e32 v186, v47, v38
	s_movk_i32 s0, 0xc0
	s_waitcnt lgkmcnt(0)
	v_mfma_f32_32x32x16_bf16 v[2:17], v[42:45], v[152:155], v[2:17]
	ds_read_b128 v[38:41], v186 offset:32768
	ds_read_b128 v[42:45], v186 offset:40960
	s_waitcnt lgkmcnt(1)
	v_mfma_f32_32x32x16_bf16 v[18:33], v[38:41], v[160:163], v[18:33]
	v_bitop3_b32 v38, v164, v46, s0 bitop3:0x36
	v_add_u32_e32 v189, v47, v38
	s_movk_i32 s0, 0xe0
	s_waitcnt lgkmcnt(0)
	v_mfma_f32_32x32x16_bf16 v[2:17], v[42:45], v[160:163], v[2:17]
	ds_read_b128 v[38:41], v189 offset:32768
	ds_read_b128 v[42:45], v189 offset:40960
	s_waitcnt lgkmcnt(1)
	v_mfma_f32_32x32x16_bf16 v[18:33], v[38:41], v[148:151], v[18:33]
	v_bitop3_b32 v38, v164, v46, s0 bitop3:0x36
	v_add_u32_e32 v190, v47, v38
	s_waitcnt lgkmcnt(0)
	v_mfma_f32_32x32x16_bf16 v[2:17], v[42:45], v[148:151], v[2:17]
	ds_read_b128 v[38:41], v190 offset:32768
	ds_read_b128 v[42:45], v190 offset:40960
	s_waitcnt lgkmcnt(1)
	v_mfma_f32_32x32x16_bf16 v[18:33], v[38:41], v[156:159], v[18:33]
	s_waitcnt lgkmcnt(0)
	v_mfma_f32_32x32x16_bf16 v[2:17], v[42:45], v[156:159], v[2:17]
	s_nop 9
	v_max_f32_e32 v38, v19, v19
	v_max_f32_e32 v39, v18, v18
	v_max_f32_e32 v38, v39, v38
	v_max3_f32 v38, v38, v20, v21
	v_max3_f32 v38, v38, v22, v23
	v_max3_f32 v38, v38, v24, v25
	v_max3_f32 v38, v38, v26, v27
	v_max3_f32 v38, v38, v28, v29
	v_max3_f32 v38, v38, v30, v31
	v_max3_f32 v38, v38, v32, v33
	v_max3_f32 v38, v38, v2, v3
	v_max3_f32 v38, v38, v4, v5
	v_max3_f32 v38, v38, v6, v7
	v_max3_f32 v38, v38, v8, v9
	v_max3_f32 v38, v38, v10, v11
	v_max3_f32 v38, v38, v12, v13
	v_max3_f32 v38, v38, v14, v15
	v_max3_f32 v38, v38, v16, v17
	v_mov_b32_e32 v39, v38
	s_nop 1
	v_permlane32_swap_b32_e32 v38, v39
	v_max_f32_e32 v39, v39, v39
	v_max_f32_e32 v38, v38, v38
	v_max_f32_e32 v38, v38, v39
	v_add_f32_e32 v39, 0x7149f2ca, v38
	v_max_f32_e32 v38, 0xf149f2ca, v38
	v_cmp_ge_f32_e32 vcc, s91, v39
	v_sub_f32_e32 v39, 0xf149f2ca, v38
	v_mul_f32_e32 v39, 0x3e0293ee, v39
	s_cmp_eq_u64 vcc, exec
	v_exp_f32_e32 v39, v39
	s_cselect_b64 vcc, -1, 0
	s_lshl_b32 s30, s28, 7
	v_cndmask_b32_e32 v193, v38, v206, vcc
	s_add_u32 s0, s96, s30
	v_mul_f32_e32 v38, 0xbe0293ee, v193
	s_addc_u32 s1, s97, 0
	v_cndmask_b32_e64 v194, v39, 1.0, vcc
	v_mov_b32_e32 v39, v38
	s_add_u32 s30, s50, s30
	v_fmac_f32_e32 v39, 0x3e0293ee, v33
	s_addc_u32 s31, s51, 0
	v_pk_fma_f32 v[98:99], v[2:3], s[90:91], v[38:39] op_sel_hi:[1,0,0]
	v_lshl_add_u64 v[2:3], s[30:31], 0, v[34:35]
	v_pk_fma_f32 v[102:103], v[6:7], s[90:91], v[38:39] op_sel_hi:[1,0,0]
	v_lshl_add_u64 v[2:3], v[2:3], 0, v[130:131]
	v_lshl_add_u64 v[6:7], s[30:31], 0, v[36:37]
	v_pk_fma_f32 v[106:107], v[10:11], s[90:91], v[38:39] op_sel_hi:[1,0,0]
	v_pk_fma_f32 v[100:101], v[4:5], s[90:91], v[38:39] op_sel_hi:[1,0,0]
	v_lshl_add_u64 v[6:7], v[6:7], 0, v[130:131]
	v_lshl_add_u64 v[10:11], s[0:1], 0, v[34:35]
	v_pk_fma_f32 v[110:111], v[14:15], s[90:91], v[38:39] op_sel_hi:[1,0,0]
	v_pk_fma_f32 v[104:105], v[8:9], s[90:91], v[38:39] op_sel_hi:[1,0,0]
	v_lshl_add_u64 v[10:11], v[10:11], 0, v[130:131]
	v_lshl_add_u64 v[14:15], s[0:1], 0, v[36:37]
	v_pk_fma_f32 v[108:109], v[12:13], s[90:91], v[38:39] op_sel_hi:[1,0,0]
	v_lshl_add_u64 v[14:15], v[14:15], 0, v[130:131]
	v_pk_fma_f32 v[112:113], v[16:17], s[90:91], v[38:39] op_sel_hi:[1,0,0]
	v_fmamk_f32 v18, v18, 0x3e0293ee, v38
	v_fmamk_f32 v19, v19, 0x3e0293ee, v38
	v_fmamk_f32 v20, v20, 0x3e0293ee, v38
	v_fmamk_f32 v21, v21, 0x3e0293ee, v38
	v_fmamk_f32 v22, v22, 0x3e0293ee, v38
	v_fmamk_f32 v23, v23, 0x3e0293ee, v38
	v_fmamk_f32 v24, v24, 0x3e0293ee, v38
	v_fmamk_f32 v25, v25, 0x3e0293ee, v38
	v_fmamk_f32 v26, v26, 0x3e0293ee, v38
	v_fmamk_f32 v27, v27, 0x3e0293ee, v38
	v_fmamk_f32 v28, v28, 0x3e0293ee, v38
	v_fmamk_f32 v29, v29, 0x3e0293ee, v38
	v_fmamk_f32 v30, v30, 0x3e0293ee, v38
	v_fmamk_f32 v31, v31, 0x3e0293ee, v38
	v_fmamk_f32 v32, v32, 0x3e0293ee, v38
	v_exp_f32_e32 v127, v18
	v_exp_f32_e32 v129, v19
	v_exp_f32_e32 v125, v20
	v_exp_f32_e32 v128, v21
	v_exp_f32_e32 v123, v22
	v_exp_f32_e32 v126, v23
	v_exp_f32_e32 v122, v24
	v_exp_f32_e32 v124, v25
	v_exp_f32_e32 v119, v26
	v_exp_f32_e32 v121, v27
	v_exp_f32_e32 v117, v28
	v_exp_f32_e32 v120, v29
	v_exp_f32_e32 v115, v30
	v_exp_f32_e32 v118, v31
	v_exp_f32_e32 v114, v32
	v_exp_f32_e32 v116, v39
	s_waitcnt vmcnt(0)
	s_waitcnt lgkmcnt(0)
	s_barrier
	v_mov_b32_e32 v17, 0
	s_cmp_lt_i32 s68, 3
	v_cmp_gt_u32_e64 s[0:1], 32, v165
	s_cbranch_scc1 .LBB0_584
	s_add_i32 s30, 0, 0x4000
	s_cmp_eq_u32 s20, 0
	v_add_u32_e32 v195, s30, v171
	s_cselect_b64 s[30:31], -1, 0
	s_lshl_b32 s38, s63, 6
	s_add_i32 s38, s69, s38
	v_lshlrev_b32_e32 v2, 2, v168
	s_add_i32 s71, s38, s22
	v_mov_b32_e32 v178, 0
	v_sub_u32_e32 v196, s71, v2
	s_sub_i32 s72, 0, s63
	s_lshl_b32 s73, s28, 8
	s_mul_i32 s74, s28, 0x180
	s_mov_b32 s75, 1
	v_mov_b32_e32 v50, 0
	v_mov_b32_e32 v51, v178
	v_mov_b32_e32 v52, v178
	v_mov_b32_e32 v53, v178
	v_mov_b32_e32 v54, v178
	v_mov_b32_e32 v55, v178
	v_mov_b32_e32 v56, v178
	v_mov_b32_e32 v57, v178
	v_mov_b32_e32 v58, v178
	v_mov_b32_e32 v59, v178
	v_mov_b32_e32 v60, v178
	v_mov_b32_e32 v61, v178
	v_mov_b32_e32 v62, v178
	v_mov_b32_e32 v63, v178
	v_mov_b32_e32 v64, v178
	v_mov_b32_e32 v65, v178
	v_mov_b32_e32 v34, 0
	v_mov_b32_e32 v35, v178
	v_mov_b32_e32 v36, v178
	v_mov_b32_e32 v37, v178
	v_mov_b32_e32 v38, v178
	v_mov_b32_e32 v39, v178
	v_mov_b32_e32 v40, v178
	v_mov_b32_e32 v41, v178
	v_mov_b32_e32 v42, v178
	v_mov_b32_e32 v43, v178
	v_mov_b32_e32 v44, v178
	v_mov_b32_e32 v45, v178
	v_mov_b32_e32 v46, v178
	v_mov_b32_e32 v47, v178
	v_mov_b32_e32 v48, v178
	v_mov_b32_e32 v49, v178
	v_mov_b32_e32 v18, 0
	v_mov_b32_e32 v19, v178
	v_mov_b32_e32 v20, v178
	v_mov_b32_e32 v21, v178
	v_mov_b32_e32 v22, v178
	v_mov_b32_e32 v23, v178
	v_mov_b32_e32 v24, v178
	v_mov_b32_e32 v25, v178
	v_mov_b32_e32 v26, v178
	v_mov_b32_e32 v27, v178
	v_mov_b32_e32 v28, v178
	v_mov_b32_e32 v29, v178
	v_mov_b32_e32 v30, v178
	v_mov_b32_e32 v31, v178
	v_mov_b32_e32 v32, v178
	v_mov_b32_e32 v33, v178
	v_mov_b32_e32 v2, 0
	v_mov_b32_e32 v3, v178
	v_mov_b32_e32 v4, v178
	v_mov_b32_e32 v5, v178
	v_mov_b32_e32 v6, v178
	v_mov_b32_e32 v7, v178
	v_mov_b32_e32 v8, v178
	v_mov_b32_e32 v9, v178
	v_mov_b32_e32 v10, v178
	v_mov_b32_e32 v11, v178
	v_mov_b32_e32 v12, v178
	v_mov_b32_e32 v13, v178
	v_mov_b32_e32 v14, v178
	v_mov_b32_e32 v15, v178
	v_mov_b32_e32 v16, v178
	v_mov_b32_e32 v17, v178
	s_cmp_lt_u32 s21, 4
	s_cbranch_scc1 .Lprio_skip
	s_setprio 1
.Lprio_skip:
.LBB0_560:
	v_exp_f32_e32 v172, v98
	v_add_f32_e32 v98, 0, v127
	v_add_f32_e32 v98, v129, v98
	v_add_f32_e32 v98, v125, v98
	v_add_f32_e32 v98, v128, v98
	v_add_f32_e32 v98, v123, v98
	v_add_f32_e32 v98, v126, v98
	v_add_f32_e32 v98, v122, v98
	v_add_f32_e32 v98, v124, v98
	v_add_f32_e32 v98, v119, v98
	v_add_f32_e32 v98, v121, v98
	v_add_f32_e32 v98, v117, v98
	v_add_f32_e32 v98, v120, v98
	v_add_f32_e32 v98, v115, v98
	v_exp_f32_e32 v173, v99
	v_add_f32_e32 v98, v118, v98
	v_exp_f32_e32 v174, v100
	v_add_f32_e32 v98, v114, v98
	v_exp_f32_e32 v175, v101
	v_add_f32_e32 v98, v116, v98
	v_exp_f32_e32 v208, v102
	v_add_f32_e32 v98, v172, v98
	v_exp_f32_e32 v209, v103
	v_add_f32_e32 v98, v173, v98
	v_exp_f32_e32 v210, v104
	v_add_f32_e32 v98, v174, v98
	v_exp_f32_e32 v211, v105
	v_add_f32_e32 v98, v175, v98
	v_exp_f32_e32 v212, v106
	v_add_f32_e32 v98, v208, v98
	v_exp_f32_e32 v213, v107
	v_add_f32_e32 v98, v209, v98
	v_exp_f32_e32 v222, v108
	v_add_f32_e32 v98, v210, v98
	v_exp_f32_e32 v223, v109
	v_add_f32_e32 v98, v211, v98
	v_exp_f32_e32 v224, v110
	v_add_f32_e32 v98, v212, v98
	v_exp_f32_e32 v225, v111
	v_add_f32_e32 v98, v213, v98
	v_exp_f32_e32 v226, v112
	v_add_f32_e32 v98, v222, v98
	v_exp_f32_e32 v113, v113
	v_add_f32_e32 v98, v223, v98
	v_add_f32_e32 v98, v224, v98
	v_add_f32_e32 v98, v225, v98
	v_add_f32_e32 v98, v226, v98
	v_add_f32_e32 v198, v113, v98
	v_mov_b32_e32 v199, v198
	v_cvt_pk_bf16_f32 v98, v127, v129
	v_cvt_pk_bf16_f32 v99, v125, v128
	v_cvt_pk_bf16_f32 v100, v123, v126
	v_cvt_pk_bf16_f32 v101, v122, v124
	v_cvt_pk_bf16_f32 v102, v119, v121
	v_cvt_pk_bf16_f32 v103, v117, v120
	v_cvt_pk_bf16_f32 v104, v115, v118
	v_cvt_pk_bf16_f32 v105, v114, v116
	v_cvt_pk_bf16_f32 v106, v172, v173
	v_cvt_pk_bf16_f32 v107, v174, v175
	v_cvt_pk_bf16_f32 v108, v208, v209
	v_cvt_pk_bf16_f32 v109, v210, v211
	v_cvt_pk_bf16_f32 v110, v212, v213
	v_cvt_pk_bf16_f32 v111, v222, v223
	v_cvt_pk_bf16_f32 v112, v224, v225
	v_cvt_pk_bf16_f32 v113, v226, v113
	s_nop 0
	v_permlane32_swap_b32_e32 v198, v199
	v_permlane32_swap_b32_e32 v98, v100
	v_permlane32_swap_b32_e32 v99, v101
	v_permlane32_swap_b32_e32 v102, v104
	v_permlane32_swap_b32_e32 v103, v105
	v_permlane32_swap_b32_e32 v106, v108
	v_permlane32_swap_b32_e32 v107, v109
	v_permlane32_swap_b32_e32 v110, v112
	v_permlane32_swap_b32_e32 v111, v113
	s_add_i32 s38, s75, 1
	s_cmp_lt_u32 s38, s63
	s_cselect_b64 s[40:41], -1, 0
	s_cmp_ge_u32 s38, s63
	s_mov_b64 s[44:45], -1
	s_cbranch_scc0 .LBB0_565
	s_add_i32 s38, s72, s75
	s_add_i32 s38, s38, 1
	s_mul_i32 s42, s38, 0x60000
	s_mul_hi_u32 s43, s38, 0x60000
	s_add_u32 s38, s78, s42
	s_addc_u32 s39, s79, s43
	s_add_u32 s42, s24, s42
	s_addc_u32 s43, s25, s43
	s_mov_b64 s[44:45], 0

.LBB0_585:
	s_setprio 0
	s_mov_b32 s75, 0xf800000
